# stack2 + P3 stage A hand-rewritten: constant read from global (no LDS staging/barrier), 64 partial loads issued up front with counted waits; same mapping and summation order
# speedup vs baseline: 1.0076x; 1.0021x over previous
.LBB0_573:
	s_lshl_b32 s28, s26, 4
	s_and_b32 s27, s28, 0x70
	s_cmpk_lt_u32 s26, 0x80
	s_cselect_b64 s[14:15], -1, 0
	s_and_b64 s[16:17], s[14:15], exec
	s_cselect_b32 s10, s1, 0x1c533400
	s_and_b32 s28, s28, 0x780
	s_lshl_b32 s98, s26, 1
	s_and_b32 s98, s98, 0xffffff00
	v_and_b32_e32 v30, 0xff, v0
	v_or_b32_e32 v30, s98, v30
	v_mov_b32_e32 v31, 0
	v_lshl_add_u64 v[30:31], v[30:31], 2, s[12:13]
	global_load_dword v126, v[30:31], off
	v_or_b32_e32 v4, s27, v15
	v_add_u32_e32 v127, s27, v15
	v_or_b32_e32 v4, s28, v4
	v_lshl_add_u64 v[8:9], v[6:7], 0, s[10:11]
	v_lshlrev_b32_e32 v4, 10, v4
	v_lshl_add_u64 v[10:11], v[8:9], 0, v[4:5]
	s_mov_b32 s98, 0x200000
	s_mov_b32 s99, 0
	s_mov_b32 s100, 0x800
	s_mov_b32 s101, 0
	global_load_ushort v32, v[10:11], off
	global_load_ushort v33, v[10:11], off offset:1536
	v_lshl_add_u64 v[12:13], v[10:11], 0, s[98:99]
	global_load_ushort v34, v[12:13], off
	global_load_ushort v35, v[12:13], off offset:1536
	v_lshl_add_u64 v[12:13], v[12:13], 0, s[98:99]
	global_load_ushort v36, v[12:13], off
	global_load_ushort v37, v[12:13], off offset:1536
	v_lshl_add_u64 v[12:13], v[12:13], 0, s[98:99]
	global_load_ushort v38, v[12:13], off
	global_load_ushort v39, v[12:13], off offset:1536
	v_lshl_add_u64 v[10:11], v[10:11], 0, s[100:101]
	global_load_ushort v40, v[10:11], off
	global_load_ushort v41, v[10:11], off offset:1536
	v_lshl_add_u64 v[12:13], v[10:11], 0, s[98:99]
	global_load_ushort v42, v[12:13], off
	global_load_ushort v43, v[12:13], off offset:1536
	v_lshl_add_u64 v[12:13], v[12:13], 0, s[98:99]
	global_load_ushort v44, v[12:13], off
	global_load_ushort v45, v[12:13], off offset:1536
	v_lshl_add_u64 v[12:13], v[12:13], 0, s[98:99]
	global_load_ushort v46, v[12:13], off
	global_load_ushort v47, v[12:13], off offset:1536
	v_lshl_add_u64 v[10:11], v[10:11], 0, s[100:101]
	global_load_ushort v48, v[10:11], off
	global_load_ushort v49, v[10:11], off offset:1536
	v_lshl_add_u64 v[12:13], v[10:11], 0, s[98:99]
	global_load_ushort v50, v[12:13], off
	global_load_ushort v51, v[12:13], off offset:1536
	v_lshl_add_u64 v[12:13], v[12:13], 0, s[98:99]
	global_load_ushort v52, v[12:13], off
	global_load_ushort v53, v[12:13], off offset:1536
	v_lshl_add_u64 v[12:13], v[12:13], 0, s[98:99]
	global_load_ushort v54, v[12:13], off
	global_load_ushort v55, v[12:13], off offset:1536
	v_lshl_add_u64 v[10:11], v[10:11], 0, s[100:101]
	global_load_ushort v56, v[10:11], off
	global_load_ushort v57, v[10:11], off offset:1536
	v_lshl_add_u64 v[12:13], v[10:11], 0, s[98:99]
	global_load_ushort v58, v[12:13], off
	global_load_ushort v59, v[12:13], off offset:1536
	v_lshl_add_u64 v[12:13], v[12:13], 0, s[98:99]
	global_load_ushort v60, v[12:13], off
	global_load_ushort v61, v[12:13], off offset:1536
	v_lshl_add_u64 v[12:13], v[12:13], 0, s[98:99]
	global_load_ushort v62, v[12:13], off
	global_load_ushort v63, v[12:13], off offset:1536
	v_lshl_add_u64 v[10:11], v[10:11], 0, s[100:101]
	global_load_ushort v64, v[10:11], off
	global_load_ushort v65, v[10:11], off offset:1536
	v_lshl_add_u64 v[12:13], v[10:11], 0, s[98:99]
	global_load_ushort v66, v[12:13], off
	global_load_ushort v67, v[12:13], off offset:1536
	v_lshl_add_u64 v[12:13], v[12:13], 0, s[98:99]
	global_load_ushort v68, v[12:13], off
	global_load_ushort v69, v[12:13], off offset:1536
	v_lshl_add_u64 v[12:13], v[12:13], 0, s[98:99]
	global_load_ushort v70, v[12:13], off
	global_load_ushort v71, v[12:13], off offset:1536
	v_lshl_add_u64 v[10:11], v[10:11], 0, s[100:101]
	global_load_ushort v72, v[10:11], off
	global_load_ushort v73, v[10:11], off offset:1536
	v_lshl_add_u64 v[12:13], v[10:11], 0, s[98:99]
	global_load_ushort v74, v[12:13], off
	global_load_ushort v75, v[12:13], off offset:1536
	v_lshl_add_u64 v[12:13], v[12:13], 0, s[98:99]
	global_load_ushort v76, v[12:13], off
	global_load_ushort v77, v[12:13], off offset:1536
	v_lshl_add_u64 v[12:13], v[12:13], 0, s[98:99]
	global_load_ushort v78, v[12:13], off
	global_load_ushort v79, v[12:13], off offset:1536
	v_lshl_add_u64 v[10:11], v[10:11], 0, s[100:101]
	global_load_ushort v80, v[10:11], off
	global_load_ushort v81, v[10:11], off offset:1536
	v_lshl_add_u64 v[12:13], v[10:11], 0, s[98:99]
	global_load_ushort v82, v[12:13], off
	global_load_ushort v83, v[12:13], off offset:1536
	v_lshl_add_u64 v[12:13], v[12:13], 0, s[98:99]
	global_load_ushort v84, v[12:13], off
	global_load_ushort v85, v[12:13], off offset:1536
	v_lshl_add_u64 v[12:13], v[12:13], 0, s[98:99]
	global_load_ushort v86, v[12:13], off
	global_load_ushort v87, v[12:13], off offset:1536
	v_lshl_add_u64 v[10:11], v[10:11], 0, s[100:101]
	s_waitcnt vmcnt(48)
	v_lshlrev_b32_e32 v32, 16, v32
	v_lshlrev_b32_e32 v33, 16, v33
	v_lshlrev_b32_e32 v34, 16, v34
	v_lshlrev_b32_e32 v35, 16, v35
	v_lshlrev_b32_e32 v36, 16, v36
	v_lshlrev_b32_e32 v37, 16, v37
	v_lshlrev_b32_e32 v38, 16, v38
	v_lshlrev_b32_e32 v39, 16, v39
	v_add_f32_e32 v96, v32, v33
	v_add_f32_e32 v97, v34, v35
	v_add_f32_e32 v98, v36, v37
	v_add_f32_e32 v99, v38, v39
	v_add_f32_e32 v100, v126, v96
	v_add_f32_e32 v100, v100, v97
	v_add_f32_e32 v100, v100, v98
	v_add_f32_e32 v100, v100, v99
	v_mul_f32_e32 v101, 0xbfb8aa3b, v100
	v_exp_f32_e32 v101, v101
	global_load_ushort v88, v[10:11], off
	global_load_ushort v89, v[10:11], off offset:1536
	v_lshl_add_u64 v[12:13], v[10:11], 0, s[98:99]
	global_load_ushort v90, v[12:13], off
	global_load_ushort v91, v[12:13], off offset:1536
	v_lshl_add_u64 v[12:13], v[12:13], 0, s[98:99]
	global_load_ushort v92, v[12:13], off
	global_load_ushort v93, v[12:13], off offset:1536
	v_lshl_add_u64 v[12:13], v[12:13], 0, s[98:99]
	global_load_ushort v94, v[12:13], off
	global_load_ushort v95, v[12:13], off offset:1536
	v_add_u32_e32 v102, 0, v127
	v_add_f32_e32 v101, 1.0, v101
	v_rcp_f32_e32 v101, v101
	v_cmp_gt_u32_e32 vcc, s0, v102
	s_nop 0
	v_mul_f32_e32 v101, v100, v101
	s_nop 0
	v_cndmask_b32_e32 v101, 0, v101, vcc
	ds_write_b32 v16, v101 offset:1024
	s_waitcnt vmcnt(48)
	v_lshlrev_b32_e32 v40, 16, v40
	v_lshlrev_b32_e32 v41, 16, v41
	v_lshlrev_b32_e32 v42, 16, v42
	v_lshlrev_b32_e32 v43, 16, v43
	v_lshlrev_b32_e32 v44, 16, v44
	v_lshlrev_b32_e32 v45, 16, v45
	v_lshlrev_b32_e32 v46, 16, v46
	v_lshlrev_b32_e32 v47, 16, v47
	v_add_f32_e32 v96, v40, v41
	v_add_f32_e32 v97, v42, v43
	v_add_f32_e32 v98, v44, v45
	v_add_f32_e32 v99, v46, v47
	v_add_f32_e32 v100, v126, v96
	v_add_f32_e32 v100, v100, v97
	v_add_f32_e32 v100, v100, v98
	v_add_f32_e32 v100, v100, v99
	v_mul_f32_e32 v101, 0xbfb8aa3b, v100
	v_exp_f32_e32 v101, v101
	v_add_u32_e32 v102, 2, v127
	v_add_f32_e32 v101, 1.0, v101
	v_rcp_f32_e32 v101, v101
	v_cmp_gt_u32_e32 vcc, s0, v102
	s_nop 0
	v_mul_f32_e32 v101, v100, v101
	s_nop 0
	v_cndmask_b32_e32 v101, 0, v101, vcc
	ds_write_b32 v16, v101 offset:1032
	s_waitcnt vmcnt(40)
	v_lshlrev_b32_e32 v48, 16, v48
	v_lshlrev_b32_e32 v49, 16, v49
	v_lshlrev_b32_e32 v50, 16, v50
	v_lshlrev_b32_e32 v51, 16, v51
	v_lshlrev_b32_e32 v52, 16, v52
	v_lshlrev_b32_e32 v53, 16, v53
	v_lshlrev_b32_e32 v54, 16, v54
	v_lshlrev_b32_e32 v55, 16, v55
	v_add_f32_e32 v96, v48, v49
	v_add_f32_e32 v97, v50, v51
	v_add_f32_e32 v98, v52, v53
	v_add_f32_e32 v99, v54, v55
	v_add_f32_e32 v100, v126, v96
	v_add_f32_e32 v100, v100, v97
	v_add_f32_e32 v100, v100, v98
	v_add_f32_e32 v100, v100, v99
	v_mul_f32_e32 v101, 0xbfb8aa3b, v100
	v_exp_f32_e32 v101, v101
	v_add_u32_e32 v102, 4, v127
	v_add_f32_e32 v101, 1.0, v101
	v_rcp_f32_e32 v101, v101
	v_cmp_gt_u32_e32 vcc, s0, v102
	s_nop 0
	v_mul_f32_e32 v101, v100, v101
	s_nop 0
	v_cndmask_b32_e32 v101, 0, v101, vcc
	ds_write_b32 v16, v101 offset:1040
	s_waitcnt vmcnt(32)
	v_lshlrev_b32_e32 v56, 16, v56
	v_lshlrev_b32_e32 v57, 16, v57
	v_lshlrev_b32_e32 v58, 16, v58
	v_lshlrev_b32_e32 v59, 16, v59
	v_lshlrev_b32_e32 v60, 16, v60
	v_lshlrev_b32_e32 v61, 16, v61
	v_lshlrev_b32_e32 v62, 16, v62
	v_lshlrev_b32_e32 v63, 16, v63
	v_add_f32_e32 v96, v56, v57
	v_add_f32_e32 v97, v58, v59
	v_add_f32_e32 v98, v60, v61
	v_add_f32_e32 v99, v62, v63
	v_add_f32_e32 v100, v126, v96
	v_add_f32_e32 v100, v100, v97
	v_add_f32_e32 v100, v100, v98
	v_add_f32_e32 v100, v100, v99
	v_mul_f32_e32 v101, 0xbfb8aa3b, v100
	v_exp_f32_e32 v101, v101
	v_add_u32_e32 v102, 6, v127
	v_add_f32_e32 v101, 1.0, v101
	v_rcp_f32_e32 v101, v101
	v_cmp_gt_u32_e32 vcc, s0, v102
	s_nop 0
	v_mul_f32_e32 v101, v100, v101
	s_nop 0
	v_cndmask_b32_e32 v101, 0, v101, vcc
	ds_write_b32 v16, v101 offset:1048
	s_waitcnt vmcnt(24)
	v_lshlrev_b32_e32 v64, 16, v64
	v_lshlrev_b32_e32 v65, 16, v65
	v_lshlrev_b32_e32 v66, 16, v66
	v_lshlrev_b32_e32 v67, 16, v67
	v_lshlrev_b32_e32 v68, 16, v68
	v_lshlrev_b32_e32 v69, 16, v69
	v_lshlrev_b32_e32 v70, 16, v70
	v_lshlrev_b32_e32 v71, 16, v71
	v_add_f32_e32 v96, v64, v65
	v_add_f32_e32 v97, v66, v67
	v_add_f32_e32 v98, v68, v69
	v_add_f32_e32 v99, v70, v71
	v_add_f32_e32 v100, v126, v96
	v_add_f32_e32 v100, v100, v97
	v_add_f32_e32 v100, v100, v98
	v_add_f32_e32 v100, v100, v99
	v_mul_f32_e32 v101, 0xbfb8aa3b, v100
	v_exp_f32_e32 v101, v101
	v_add_u32_e32 v102, 8, v127
	v_add_f32_e32 v101, 1.0, v101
	v_rcp_f32_e32 v101, v101
	v_cmp_gt_u32_e32 vcc, s0, v102
	s_nop 0
	v_mul_f32_e32 v101, v100, v101
	s_nop 0
	v_cndmask_b32_e32 v101, 0, v101, vcc
	ds_write_b32 v16, v101 offset:1056
	s_waitcnt vmcnt(16)
	v_lshlrev_b32_e32 v72, 16, v72
	v_lshlrev_b32_e32 v73, 16, v73
	v_lshlrev_b32_e32 v74, 16, v74
	v_lshlrev_b32_e32 v75, 16, v75
	v_lshlrev_b32_e32 v76, 16, v76
	v_lshlrev_b32_e32 v77, 16, v77
	v_lshlrev_b32_e32 v78, 16, v78
	v_lshlrev_b32_e32 v79, 16, v79
	v_add_f32_e32 v96, v72, v73
	v_add_f32_e32 v97, v74, v75
	v_add_f32_e32 v98, v76, v77
	v_add_f32_e32 v99, v78, v79
	v_add_f32_e32 v100, v126, v96
	v_add_f32_e32 v100, v100, v97
	v_add_f32_e32 v100, v100, v98
	v_add_f32_e32 v100, v100, v99
	v_mul_f32_e32 v101, 0xbfb8aa3b, v100
	v_exp_f32_e32 v101, v101
	v_add_u32_e32 v102, 10, v127
	v_add_f32_e32 v101, 1.0, v101
	v_rcp_f32_e32 v101, v101
	v_cmp_gt_u32_e32 vcc, s0, v102
	s_nop 0
	v_mul_f32_e32 v101, v100, v101
	s_nop 0
	v_cndmask_b32_e32 v101, 0, v101, vcc
	ds_write_b32 v16, v101 offset:1064
	s_waitcnt vmcnt(8)
	v_lshlrev_b32_e32 v80, 16, v80
	v_lshlrev_b32_e32 v81, 16, v81
	v_lshlrev_b32_e32 v82, 16, v82
	v_lshlrev_b32_e32 v83, 16, v83
	v_lshlrev_b32_e32 v84, 16, v84
	v_lshlrev_b32_e32 v85, 16, v85
	v_lshlrev_b32_e32 v86, 16, v86
	v_lshlrev_b32_e32 v87, 16, v87
	v_add_f32_e32 v96, v80, v81
	v_add_f32_e32 v97, v82, v83
	v_add_f32_e32 v98, v84, v85
	v_add_f32_e32 v99, v86, v87
	v_add_f32_e32 v100, v126, v96
	v_add_f32_e32 v100, v100, v97
	v_add_f32_e32 v100, v100, v98
	v_add_f32_e32 v100, v100, v99
	v_mul_f32_e32 v101, 0xbfb8aa3b, v100
	v_exp_f32_e32 v101, v101
	v_add_u32_e32 v102, 12, v127
	v_add_f32_e32 v101, 1.0, v101
	v_rcp_f32_e32 v101, v101
	v_cmp_gt_u32_e32 vcc, s0, v102
	s_nop 0
	v_mul_f32_e32 v101, v100, v101
	s_nop 0
	v_cndmask_b32_e32 v101, 0, v101, vcc
	ds_write_b32 v16, v101 offset:1072
	s_waitcnt vmcnt(0)
	v_lshlrev_b32_e32 v88, 16, v88
	v_lshlrev_b32_e32 v89, 16, v89
	v_lshlrev_b32_e32 v90, 16, v90
	v_lshlrev_b32_e32 v91, 16, v91
	v_lshlrev_b32_e32 v92, 16, v92
	v_lshlrev_b32_e32 v93, 16, v93
	v_lshlrev_b32_e32 v94, 16, v94
	v_lshlrev_b32_e32 v95, 16, v95
	v_add_f32_e32 v96, v88, v89
	v_add_f32_e32 v97, v90, v91
	v_add_f32_e32 v98, v92, v93
	v_add_f32_e32 v99, v94, v95
	v_add_f32_e32 v100, v126, v96
	v_add_f32_e32 v100, v100, v97
	v_add_f32_e32 v100, v100, v98
	v_add_f32_e32 v100, v100, v99
	v_mul_f32_e32 v101, 0xbfb8aa3b, v100
	v_exp_f32_e32 v101, v101
	v_add_u32_e32 v102, 14, v127
	v_add_f32_e32 v101, 1.0, v101
	v_rcp_f32_e32 v101, v101
	v_cmp_gt_u32_e32 vcc, s0, v102
	s_nop 0
	v_mul_f32_e32 v101, v100, v101
	s_nop 0
	v_cndmask_b32_e32 v101, 0, v101, vcc
	ds_write_b32 v16, v101 offset:1080
.LBB0_583:
	s_and_b64 s[16:17], s[14:15], exec
	s_cselect_b32 s17, s7, s9
	s_cselect_b32 s16, s6, s8
	v_lshlrev_b32_e32 v4, 2, v2
	v_mov_b32_e32 v12, 0
	v_lshl_add_u64 v[8:9], s[16:17], 0, v[4:5]
	s_mov_b64 s[16:17], 0
	v_mov_b32_e32 v4, v28
	v_mov_b32_e32 v13, v12
	v_mov_b32_e32 v10, v12
	v_mov_b32_e32 v11, v12
	s_waitcnt lgkmcnt(0)
	s_barrier
